# v025 + cross prompt units only: z-gate tile staged in LDS by LDS-DMA in the last tile iteration, epilogue reads it with ds_read_u16
# speedup vs baseline: 1.0229x; 1.0074x over previous
; DI float bf2f(unsigned short u) { return __uint_as_float((unsigned)u << 16); }
; DI unsigned f2bf(float f) { unsigned u = __float_as_uint(f); return (u + 0x7fffu + ((u >> 16) & 1u)) >> 16; }
; DI int crow(int i, int hh) { return (i & 3) + 8 * (i >> 2) + 4 * hh; }
; DI void cross_unit(Ctx A_, LAS unsigned char* lds, int kvb, int hc, size_t row0, int nrows, int wave, int lane) {
;     ...
;     if (act) {
;         l += __shfl_xor(l, 32);
;         if (hh == 0) wsf[32 + r] = l;
;         float rl[16];
; #pragma unroll
;         for (int i = 0; i < 16; ++i) rl[i] = 1.0f / wsf[32 + crow(i, hh)];
; #pragma unroll
;         for (int nb = 0; nb < 4; ++nb)
; #pragma unroll
;             for (int i = 0; i < 16; ++i) {
;                 const int q = rg * 32 + crow(i, hh);
;                 if (q < nrows) { const size_t eo = (row0 + q) * PLD + hc * 256 + dvh * 128 + nb * 32 + r; Y_[(row0 + q) * YLD + C_YC + hc * 256 + dvh * 128 + nb * 32 + r] = (bf16)f2bf(o[nb][i] * rl[i] * bf2f(P[eo + C_ZC])); }
;             }
.LBB0_897:
	s_or_b64 exec, exec, s[34:35]
	s_waitcnt vmcnt(0)
	v_and_b32_e32 v206, 63, v0
	v_lshrrev_b32_e32 v207, 5, v206
	v_and_b32_e32 v206, 31, v206
	v_lshlrev_b32_e32 v206, 1, v206
	v_lshl_or_b32 v206, v207, 10, v206
	v_readfirstlane_b32 s98, v0
	s_lshr_b32 s98, s98, 6
	s_lshl_b32 s98, s98, 13
	s_add_i32 s98, s98, 0x10000
	v_add_u32_e32 v206, s98, v206
	s_lshl_b32 s4, s64, 1
	s_add_u32 s34, s49, s4
	v_lshl_or_b32 v4, v174, 2, s44
	s_addc_u32 s35, s50, 0
	s_waitcnt lgkmcnt(0)
	v_lshlrev_b32_e32 v2, 1, v164
	v_lshl_add_u64 v[8:9], s[34:35], 0, v[2:3]
	v_or_b32_e32 v82, s30, v4
	v_mad_u64_u32 v[4:5], s[34:35], v82, s59, v[8:9]
	s_mul_i32 s2, s31, 0x5800
	v_add_u32_e32 v5, s2, v5
	v_add_co_u32_e32 v4, vcc, s60, v4
	v_add_u32_e32 v101, s40, v162
	s_nop 0
	v_addc_co_u32_e32 v5, vcc, 0, v5, vcc
	ds_read_u16 v83, v206 offset:0
	ds_read_u16 v98, v206 offset:64
	ds_read_u16 v99, v206 offset:128
	ds_read_u16 v100, v206 offset:192
	ds_read_b128 v[84:87], v101 offset:128
	ds_read_b128 v[4:7], v101 offset:160
	s_add_u32 s34, s53, s4
	s_addc_u32 s35, s54, 0
	v_lshl_add_u64 v[10:11], s[34:35], 0, v[2:3]
	s_add_u32 s34, s51, s4
	s_waitcnt lgkmcnt(1)
	v_div_scale_f32 v103, s[4:5], v84, v84, 1.0
	v_rcp_f32_e32 v105, v103
	v_or_b32_e32 v102, 1, v82
	v_mad_u64_u32 v[12:13], s[64:65], v102, s59, v[8:9]
	v_mad_u64_u32 v[88:89], s[4:5], v82, s62, v[10:11]
	v_add_u32_e32 v13, s2, v13
	v_add_co_u32_e64 v90, s[4:5], s60, v12
	s_addc_u32 s35, s52, 0
	s_nop 0
	v_addc_co_u32_e64 v91, s[4:5], 0, v13, s[4:5]
	v_lshl_add_u64 v[12:13], s[34:35], 0, v[2:3]
	v_fma_f32 v2, -v103, v105, 1.0
	v_div_scale_f32 v104, vcc, 1.0, v84, 1.0
	v_fmac_f32_e32 v105, v2, v105
	v_mul_f32_e32 v2, v104, v105
	v_fma_f32 v106, -v103, v2, v104
	v_fmac_f32_e32 v2, v106, v105
	v_fma_f32 v103, -v103, v2, v104
	v_div_fmas_f32 v2, v103, v105, v2
	v_div_fixup_f32 v2, v2, v84, 1.0
	v_mul_f32_e32 v18, v18, v2
	v_mul_f32_e32 v34, v34, v2
	v_mul_f32_e32 v50, v50, v2
	v_mul_f32_e32 v2, v66, v2
	s_mul_i32 s30, s31, 0x1800
	v_lshl_add_u64 v[14:15], v[12:13], 0, s[24:25]
	v_lshl_add_u64 v[16:17], v[12:13], 0, s[26:27]
	v_lshl_add_u64 v[12:13], v[12:13], 0, s[28:29]
	v_add_u32_e32 v89, s30, v89
	v_mad_u64_u32 v[92:93], s[4:5], v82, s62, v[14:15]
	v_mad_u64_u32 v[94:95], s[4:5], v82, s62, v[16:17]
	v_mad_u64_u32 v[96:97], s[4:5], v82, s62, v[12:13]
	v_add_u32_e32 v93, s30, v93
	v_add_u32_e32 v95, s30, v95
	v_add_u32_e32 v97, s30, v97
	s_waitcnt lgkmcnt(0)
	v_lshlrev_b32_e32 v66, 16, v83
	s_waitcnt lgkmcnt(0)
	v_lshlrev_b32_e32 v83, 16, v98
	s_waitcnt lgkmcnt(0)
	v_lshlrev_b32_e32 v84, 16, v99
	s_waitcnt lgkmcnt(0)
	v_lshlrev_b32_e32 v98, 16, v100
	v_mul_f32_e32 v18, v18, v66
	v_mul_f32_e32 v34, v34, v83
	v_mul_f32_e32 v50, v50, v84
	v_mul_f32_e32 v2, v2, v98
	v_bfe_u32 v66, v18, 16, 1
	v_bfe_u32 v83, v34, 16, 1
	v_bfe_u32 v84, v50, 16, 1
	v_bfe_u32 v98, v2, 16, 1
	v_add3_u32 v18, v18, v66, s61
	v_add3_u32 v34, v34, v83, s61
	v_add3_u32 v50, v50, v84, s61
	v_add3_u32 v2, v2, v98, s61
	global_store_short_d16_hi v[88:89], v18, off
	global_store_short_d16_hi v[92:93], v34, off
	global_store_short_d16_hi v[94:95], v50, off
	global_store_short_d16_hi v[96:97], v2, off
	ds_read_u16 v2, v206 offset:256
	s_nop 0
	ds_read_u16 v18, v206 offset:320
	ds_read_u16 v34, v206 offset:384
	ds_read_u16 v50, v206 offset:448
	v_or_b32_e32 v83, 2, v82
	v_mad_u64_u32 v[88:89], s[4:5], v83, s59, v[8:9]
	v_div_scale_f32 v84, s[4:5], v85, v85, 1.0
	v_mad_u64_u32 v[90:91], s[4:5], v102, s62, v[10:11]
	v_add_u32_e32 v66, s2, v89
	v_add_co_u32_e64 v88, s[4:5], s60, v88
	v_div_scale_f32 v98, vcc, 1.0, v85, 1.0
	s_nop 0
	v_addc_co_u32_e64 v89, s[4:5], 0, v66, s[4:5]
	v_rcp_f32_e32 v66, v84
	v_add_u32_e32 v91, s30, v91
	v_mad_u64_u32 v[92:93], s[4:5], v102, s62, v[14:15]
	v_fma_f32 v99, -v84, v66, 1.0
	v_fmac_f32_e32 v66, v99, v66
	v_mul_f32_e32 v99, v98, v66
	v_fma_f32 v100, -v84, v99, v98
	v_fmac_f32_e32 v99, v100, v66
	v_fma_f32 v84, -v84, v99, v98
	v_div_fmas_f32 v66, v84, v66, v99
	v_div_fixup_f32 v66, v66, v85, 1.0
	v_mul_f32_e32 v19, v19, v66
	v_mul_f32_e32 v35, v35, v66
	v_mul_f32_e32 v51, v51, v66
	v_mul_f32_e32 v66, v67, v66
	v_mad_u64_u32 v[94:95], s[4:5], v102, s62, v[16:17]
	v_mad_u64_u32 v[96:97], s[4:5], v102, s62, v[12:13]
	v_add_u32_e32 v93, s30, v93
	v_add_u32_e32 v95, s30, v95
	v_add_u32_e32 v97, s30, v97
	s_waitcnt lgkmcnt(0)
	v_lshlrev_b32_e32 v2, 16, v2
	s_waitcnt lgkmcnt(0)
	v_lshlrev_b32_e32 v18, 16, v18
	s_waitcnt lgkmcnt(0)
	v_lshlrev_b32_e32 v34, 16, v34
	s_waitcnt lgkmcnt(0)
	v_lshlrev_b32_e32 v50, 16, v50
	v_mul_f32_e32 v2, v19, v2
	v_mul_f32_e32 v18, v35, v18
	v_mul_f32_e32 v19, v51, v34
	v_mul_f32_e32 v34, v66, v50
	v_bfe_u32 v35, v2, 16, 1
	v_bfe_u32 v50, v18, 16, 1
	v_bfe_u32 v51, v19, 16, 1
	v_bfe_u32 v66, v34, 16, 1
	v_add3_u32 v2, v2, v35, s61
	v_add3_u32 v18, v18, v50, s61
	v_add3_u32 v19, v19, v51, s61
	v_add3_u32 v34, v34, v66, s61
	global_store_short_d16_hi v[90:91], v2, off
	global_store_short_d16_hi v[92:93], v18, off
	global_store_short_d16_hi v[94:95], v19, off
	global_store_short_d16_hi v[96:97], v34, off
	ds_read_u16 v2, v206 offset:512
	s_nop 0
	ds_read_u16 v90, v206 offset:576
	ds_read_u16 v91, v206 offset:640
	s_nop 0
	ds_read_u16 v88, v206 offset:704
	v_div_scale_f32 v92, s[4:5], v86, v86, 1.0
	v_rcp_f32_e32 v94, v92
	v_or_b32_e32 v89, 3, v82
	v_mad_u64_u32 v[18:19], s[4:5], v89, s59, v[8:9]
	v_mad_u64_u32 v[34:35], s[4:5], v83, s62, v[10:11]
	v_add_u32_e32 v19, s2, v19
	v_add_co_u32_e64 v18, s[4:5], s60, v18
	v_div_scale_f32 v93, vcc, 1.0, v86, 1.0
	s_nop 0
	v_addc_co_u32_e64 v19, s[4:5], 0, v19, s[4:5]
	v_mad_u64_u32 v[50:51], s[4:5], v83, s62, v[14:15]
	v_mad_u64_u32 v[66:67], s[4:5], v83, s62, v[16:17]
	v_mad_u64_u32 v[84:85], s[4:5], v83, s62, v[12:13]
	v_fma_f32 v83, -v92, v94, 1.0
	v_fmac_f32_e32 v94, v83, v94
	v_mul_f32_e32 v83, v93, v94
	v_fma_f32 v95, -v92, v83, v93
	v_fmac_f32_e32 v83, v95, v94
	v_fma_f32 v92, -v92, v83, v93
	v_div_fmas_f32 v83, v92, v94, v83
	v_div_fixup_f32 v83, v83, v86, 1.0
	v_mul_f32_e32 v20, v20, v83
	v_mul_f32_e32 v36, v36, v83
	v_mul_f32_e32 v52, v52, v83
	v_mul_f32_e32 v68, v68, v83
	v_add_u32_e32 v35, s30, v35
	v_add_u32_e32 v51, s30, v51
	v_add_u32_e32 v67, s30, v67
	v_add_u32_e32 v85, s30, v85
	s_waitcnt lgkmcnt(0)
; DI float bf2f(unsigned short u) { return __uint_as_float((unsigned)u << 16); }
; DI unsigned f2bf(float f) { unsigned u = __float_as_uint(f); return (u + 0x7fffu + ((u >> 16) & 1u)) >> 16; }
; DI int crow(int i, int hh) { return (i & 3) + 8 * (i >> 2) + 4 * hh; }
; DI void cross_unit(Ctx A_, LAS unsigned char* lds, int kvb, int hc, size_t row0, int nrows, int wave, int lane) {
;     ...
;     if (act) {
;         l += __shfl_xor(l, 32);
;         if (hh == 0) wsf[32 + r] = l;
;         float rl[16];
; #pragma unroll
;         for (int i = 0; i < 16; ++i) rl[i] = 1.0f / wsf[32 + crow(i, hh)];
; #pragma unroll
;         for (int nb = 0; nb < 4; ++nb)
; #pragma unroll
;             for (int i = 0; i < 16; ++i) {
;                 const int q = rg * 32 + crow(i, hh);
;                 if (q < nrows) { const size_t eo = (row0 + q) * PLD + hc * 256 + dvh * 128 + nb * 32 + r; Y_[(row0 + q) * YLD + C_YC + hc * 256 + dvh * 128 + nb * 32 + r] = (bf16)f2bf(o[nb][i] * rl[i] * bf2f(P[eo + C_ZC])); }
;             }
	v_lshlrev_b32_e32 v2, 16, v2
	s_waitcnt lgkmcnt(0)
	v_lshlrev_b32_e32 v83, 16, v90
	s_waitcnt lgkmcnt(0)
	v_lshlrev_b32_e32 v86, 16, v91
	s_waitcnt lgkmcnt(0)
	v_lshlrev_b32_e32 v88, 16, v88
	v_mul_f32_e32 v2, v20, v2
	v_mul_f32_e32 v20, v36, v83
	v_mul_f32_e32 v36, v52, v86
	v_mul_f32_e32 v52, v68, v88
	v_bfe_u32 v68, v2, 16, 1
	v_bfe_u32 v83, v20, 16, 1
	v_bfe_u32 v86, v36, 16, 1
	v_bfe_u32 v88, v52, 16, 1
	v_add3_u32 v2, v2, v68, s61
	v_add3_u32 v20, v20, v83, s61
	v_add3_u32 v36, v36, v86, s61
	v_add3_u32 v52, v52, v88, s61
	global_store_short_d16_hi v[34:35], v2, off
	global_store_short_d16_hi v[50:51], v20, off
	global_store_short_d16_hi v[66:67], v36, off
	global_store_short_d16_hi v[84:85], v52, off
	ds_read_u16 v2, v206 offset:768
	s_nop 0
	ds_read_u16 v20, v206 offset:832
	ds_read_u16 v36, v206 offset:896
	ds_read_u16 v52, v206 offset:960
	v_div_scale_f32 v83, s[4:5], v87, v87, 1.0
	v_rcp_f32_e32 v88, v83
	v_or_b32_e32 v68, 8, v82
	v_mad_u64_u32 v[18:19], s[4:5], v68, s59, v[8:9]
	v_mad_u64_u32 v[34:35], s[4:5], v89, s62, v[10:11]
	v_add_u32_e32 v19, s2, v19
	v_add_co_u32_e64 v18, s[4:5], s60, v18
	v_div_scale_f32 v86, vcc, 1.0, v87, 1.0
	s_nop 0
	v_addc_co_u32_e64 v19, s[4:5], 0, v19, s[4:5]
	v_mad_u64_u32 v[50:51], s[4:5], v89, s62, v[14:15]
	v_mad_u64_u32 v[66:67], s[4:5], v89, s62, v[16:17]
	v_mad_u64_u32 v[84:85], s[4:5], v89, s62, v[12:13]
	v_fma_f32 v89, -v83, v88, 1.0
	v_fmac_f32_e32 v88, v89, v88
	v_mul_f32_e32 v89, v86, v88
	v_fma_f32 v90, -v83, v89, v86
	v_fmac_f32_e32 v89, v90, v88
	v_fma_f32 v83, -v83, v89, v86
	v_div_fmas_f32 v83, v83, v88, v89
	v_div_fixup_f32 v83, v83, v87, 1.0
	v_mul_f32_e32 v21, v21, v83
	v_mul_f32_e32 v37, v37, v83
	v_mul_f32_e32 v53, v53, v83
	v_mul_f32_e32 v69, v69, v83
	v_add_u32_e32 v35, s30, v35
	v_add_u32_e32 v51, s30, v51
	v_add_u32_e32 v67, s30, v67
	v_add_u32_e32 v85, s30, v85
	s_waitcnt lgkmcnt(0)
	v_div_scale_f32 v83, vcc, 1.0, v4, 1.0
	s_waitcnt lgkmcnt(0)
	v_lshlrev_b32_e32 v2, 16, v2
	s_waitcnt lgkmcnt(0)
	v_lshlrev_b32_e32 v20, 16, v20
	s_waitcnt lgkmcnt(0)
	v_lshlrev_b32_e32 v36, 16, v36
	s_waitcnt lgkmcnt(0)
	v_lshlrev_b32_e32 v52, 16, v52
	v_mul_f32_e32 v2, v21, v2
	v_mul_f32_e32 v20, v37, v20
	v_mul_f32_e32 v21, v53, v36
	v_mul_f32_e32 v36, v69, v52
	v_bfe_u32 v37, v2, 16, 1
	v_bfe_u32 v52, v20, 16, 1
	v_bfe_u32 v53, v21, 16, 1
	v_bfe_u32 v69, v36, 16, 1
	v_add3_u32 v2, v2, v37, s61
	v_add3_u32 v20, v20, v52, s61
	v_add3_u32 v21, v21, v53, s61
	v_add3_u32 v36, v36, v69, s61
	global_store_short_d16_hi v[34:35], v2, off
	global_store_short_d16_hi v[50:51], v20, off
	global_store_short_d16_hi v[66:67], v21, off
	global_store_short_d16_hi v[84:85], v36, off
	ds_read_u16 v2, v206 offset:2048
	s_nop 0
	ds_read_u16 v52, v206 offset:2112
	ds_read_u16 v53, v206 offset:2176
	ds_read_u16 v66, v206 offset:2240
	v_div_scale_f32 v69, s[4:5], v4, v4, 1.0
	v_rcp_f32_e32 v84, v69
	v_or_b32_e32 v67, 9, v82
	v_mad_u64_u32 v[18:19], s[4:5], v67, s59, v[8:9]
	v_mad_u64_u32 v[20:21], s[4:5], v68, s62, v[10:11]
	v_add_u32_e32 v19, s2, v19
	v_add_co_u32_e64 v18, s[4:5], s60, v18
	v_add_u32_e32 v21, s30, v21
	s_nop 0
	v_addc_co_u32_e64 v19, s[4:5], 0, v19, s[4:5]
	v_mad_u64_u32 v[34:35], s[4:5], v68, s62, v[14:15]
	v_mad_u64_u32 v[36:37], s[4:5], v68, s62, v[16:17]
	v_mad_u64_u32 v[50:51], s[4:5], v68, s62, v[12:13]
	v_fma_f32 v68, -v69, v84, 1.0
	v_fmac_f32_e32 v84, v68, v84
	v_mul_f32_e32 v68, v83, v84
	v_fma_f32 v85, -v69, v68, v83
	v_fmac_f32_e32 v68, v85, v84
	v_fma_f32 v69, -v69, v68, v83
	v_div_fmas_f32 v68, v69, v84, v68
	v_div_fixup_f32 v4, v68, v4, 1.0
	v_mul_f32_e32 v22, v22, v4
	v_mul_f32_e32 v38, v38, v4
	v_mul_f32_e32 v54, v54, v4
	v_mul_f32_e32 v4, v70, v4
	v_add_u32_e32 v35, s30, v35
	v_add_u32_e32 v37, s30, v37
	v_add_u32_e32 v51, s30, v51
	s_waitcnt lgkmcnt(0)
	v_lshlrev_b32_e32 v2, 16, v2
	s_waitcnt lgkmcnt(0)
	v_lshlrev_b32_e32 v52, 16, v52
	s_waitcnt lgkmcnt(0)
	v_lshlrev_b32_e32 v53, 16, v53
	s_waitcnt lgkmcnt(0)
	v_lshlrev_b32_e32 v66, 16, v66
	v_mul_f32_e32 v2, v22, v2
	v_mul_f32_e32 v22, v38, v52
	v_mul_f32_e32 v38, v54, v53
	v_mul_f32_e32 v4, v4, v66
	v_bfe_u32 v52, v2, 16, 1
	v_bfe_u32 v53, v22, 16, 1
	v_bfe_u32 v54, v38, 16, 1
	v_bfe_u32 v66, v4, 16, 1
	v_add3_u32 v2, v2, v52, s61
	v_add3_u32 v22, v22, v53, s61
	v_add3_u32 v38, v38, v54, s61
	v_add3_u32 v4, v4, v66, s61
	global_store_short_d16_hi v[20:21], v2, off
	global_store_short_d16_hi v[34:35], v22, off
	global_store_short_d16_hi v[36:37], v38, off
	global_store_short_d16_hi v[50:51], v4, off
	ds_read_u16 v2, v206 offset:2304
	s_nop 0
	ds_read_u16 v4, v206 offset:2368
	ds_read_u16 v22, v206 offset:2432
	ds_read_u16 v38, v206 offset:2496
	v_div_scale_f32 v53, s[4:5], v5, v5, 1.0
	v_rcp_f32_e32 v66, v53
	v_or_b32_e32 v52, 10, v82
	v_mad_u64_u32 v[18:19], s[4:5], v52, s59, v[8:9]
	v_mad_u64_u32 v[20:21], s[4:5], v67, s62, v[10:11]
	v_add_u32_e32 v19, s2, v19
	v_add_co_u32_e64 v18, s[4:5], s60, v18
	v_div_scale_f32 v54, vcc, 1.0, v5, 1.0
	s_nop 0
	v_addc_co_u32_e64 v19, s[4:5], 0, v19, s[4:5]
	v_mad_u64_u32 v[34:35], s[4:5], v67, s62, v[14:15]
	v_mad_u64_u32 v[36:37], s[4:5], v67, s62, v[16:17]
	v_mad_u64_u32 v[50:51], s[4:5], v67, s62, v[12:13]
	v_fma_f32 v67, -v53, v66, 1.0
	v_fmac_f32_e32 v66, v67, v66
	v_mul_f32_e32 v67, v54, v66
	v_fma_f32 v68, -v53, v67, v54
	v_fmac_f32_e32 v67, v68, v66
	v_fma_f32 v53, -v53, v67, v54
	v_div_fmas_f32 v53, v53, v66, v67
	v_div_fixup_f32 v5, v53, v5, 1.0
	v_mul_f32_e32 v23, v23, v5
	v_mul_f32_e32 v39, v39, v5
	v_mul_f32_e32 v53, v55, v5
	v_mul_f32_e32 v5, v71, v5
	v_add_u32_e32 v21, s30, v21
	v_add_u32_e32 v35, s30, v35
	v_add_u32_e32 v37, s30, v37
	v_add_u32_e32 v51, s30, v51
	s_waitcnt lgkmcnt(0)
; DI float bf2f(unsigned short u) { return __uint_as_float((unsigned)u << 16); }
; DI unsigned f2bf(float f) { unsigned u = __float_as_uint(f); return (u + 0x7fffu + ((u >> 16) & 1u)) >> 16; }
; DI int crow(int i, int hh) { return (i & 3) + 8 * (i >> 2) + 4 * hh; }
; DI void cross_unit(Ctx A_, LAS unsigned char* lds, int kvb, int hc, size_t row0, int nrows, int wave, int lane) {
;     ...
;     if (act) {
;         l += __shfl_xor(l, 32);
;         if (hh == 0) wsf[32 + r] = l;
;         float rl[16];
; #pragma unroll
;         for (int i = 0; i < 16; ++i) rl[i] = 1.0f / wsf[32 + crow(i, hh)];
; #pragma unroll
;         for (int nb = 0; nb < 4; ++nb)
; #pragma unroll
;             for (int i = 0; i < 16; ++i) {
;                 const int q = rg * 32 + crow(i, hh);
;                 if (q < nrows) { const size_t eo = (row0 + q) * PLD + hc * 256 + dvh * 128 + nb * 32 + r; Y_[(row0 + q) * YLD + C_YC + hc * 256 + dvh * 128 + nb * 32 + r] = (bf16)f2bf(o[nb][i] * rl[i] * bf2f(P[eo + C_ZC])); }
;             }
	v_lshlrev_b32_e32 v2, 16, v2
	s_waitcnt lgkmcnt(0)
	v_lshlrev_b32_e32 v4, 16, v4
	s_waitcnt lgkmcnt(0)
	v_lshlrev_b32_e32 v22, 16, v22
	s_waitcnt lgkmcnt(0)
	v_lshlrev_b32_e32 v38, 16, v38
	v_mul_f32_e32 v2, v23, v2
	v_mul_f32_e32 v4, v39, v4
	v_mul_f32_e32 v22, v53, v22
	v_mul_f32_e32 v5, v5, v38
	v_bfe_u32 v23, v2, 16, 1
	v_bfe_u32 v38, v4, 16, 1
	v_bfe_u32 v39, v22, 16, 1
	v_bfe_u32 v53, v5, 16, 1
	v_add3_u32 v2, v2, v23, s61
	v_add3_u32 v4, v4, v38, s61
	v_add3_u32 v22, v22, v39, s61
	v_add3_u32 v5, v5, v53, s61
	global_store_short_d16_hi v[20:21], v2, off
	global_store_short_d16_hi v[34:35], v4, off
	global_store_short_d16_hi v[36:37], v22, off
	global_store_short_d16_hi v[50:51], v5, off
	ds_read_u16 v2, v206 offset:2560
	s_nop 0
	ds_read_u16 v36, v206 offset:2624
	ds_read_u16 v37, v206 offset:2688
	ds_read_u16 v38, v206 offset:2752
	v_div_scale_f32 v50, s[4:5], v6, v6, 1.0
	v_rcp_f32_e32 v53, v50
	v_or_b32_e32 v39, 11, v82
	v_mad_u64_u32 v[4:5], s[4:5], v39, s59, v[8:9]
	v_mad_u64_u32 v[18:19], s[4:5], v52, s62, v[10:11]
	v_add_u32_e32 v5, s2, v5
	v_add_co_u32_e64 v4, s[4:5], s60, v4
	v_div_scale_f32 v51, vcc, 1.0, v6, 1.0
	s_nop 0
	v_addc_co_u32_e64 v5, s[4:5], 0, v5, s[4:5]
	v_mad_u64_u32 v[20:21], s[4:5], v52, s62, v[14:15]
	v_mad_u64_u32 v[22:23], s[4:5], v52, s62, v[16:17]
	v_mad_u64_u32 v[34:35], s[4:5], v52, s62, v[12:13]
	v_fma_f32 v52, -v50, v53, 1.0
	v_fmac_f32_e32 v53, v52, v53
	v_mul_f32_e32 v52, v51, v53
	v_fma_f32 v54, -v50, v52, v51
	v_fmac_f32_e32 v52, v54, v53
	v_fma_f32 v50, -v50, v52, v51
	v_div_fmas_f32 v50, v50, v53, v52
	v_div_fixup_f32 v6, v50, v6, 1.0
	v_mul_f32_e32 v24, v24, v6
	v_mul_f32_e32 v40, v40, v6
	v_mul_f32_e32 v50, v56, v6
	v_mul_f32_e32 v6, v72, v6
	v_add_u32_e32 v19, s30, v19
	v_add_u32_e32 v21, s30, v21
	v_add_u32_e32 v23, s30, v23
	v_add_u32_e32 v35, s30, v35
	s_waitcnt lgkmcnt(0)
	v_lshlrev_b32_e32 v2, 16, v2
	s_waitcnt lgkmcnt(0)
	v_lshlrev_b32_e32 v36, 16, v36
	s_waitcnt lgkmcnt(0)
	v_lshlrev_b32_e32 v37, 16, v37
	s_waitcnt lgkmcnt(0)
	v_lshlrev_b32_e32 v38, 16, v38
	v_mul_f32_e32 v2, v24, v2
	v_mul_f32_e32 v24, v40, v36
	v_mul_f32_e32 v36, v50, v37
	v_mul_f32_e32 v6, v6, v38
	v_bfe_u32 v37, v2, 16, 1
	v_bfe_u32 v38, v24, 16, 1
	v_bfe_u32 v40, v36, 16, 1
	v_bfe_u32 v50, v6, 16, 1
	v_add3_u32 v2, v2, v37, s61
	v_add3_u32 v24, v24, v38, s61
	v_add3_u32 v36, v36, v40, s61
	v_add3_u32 v6, v6, v50, s61
	global_store_short_d16_hi v[18:19], v2, off
	global_store_short_d16_hi v[20:21], v24, off
	global_store_short_d16_hi v[22:23], v36, off
	global_store_short_d16_hi v[34:35], v6, off
	ds_read_u16 v2, v206 offset:2816
	s_nop 0
	ds_read_u16 v6, v206 offset:2880
	ds_read_u16 v24, v206 offset:2944
	ds_read_u16 v36, v206 offset:3008
	v_div_scale_f32 v37, s[4:5], v7, v7, 1.0
	v_rcp_f32_e32 v50, v37
	v_or_b32_e32 v38, 16, v82
	v_mad_u64_u32 v[4:5], s[4:5], v38, s59, v[8:9]
	v_mad_u64_u32 v[18:19], s[4:5], v39, s62, v[10:11]
	v_add_u32_e32 v5, s2, v5
	v_add_co_u32_e64 v4, s[4:5], s60, v4
	v_div_scale_f32 v40, vcc, 1.0, v7, 1.0
	s_nop 0
	v_addc_co_u32_e64 v5, s[4:5], 0, v5, s[4:5]
	v_mad_u64_u32 v[20:21], s[4:5], v39, s62, v[14:15]
	v_mad_u64_u32 v[22:23], s[4:5], v39, s62, v[16:17]
	v_mad_u64_u32 v[34:35], s[4:5], v39, s62, v[12:13]
	v_fma_f32 v39, -v37, v50, 1.0
	v_fmac_f32_e32 v50, v39, v50
	v_mul_f32_e32 v39, v40, v50
	v_fma_f32 v51, -v37, v39, v40
	v_fmac_f32_e32 v39, v51, v50
	v_fma_f32 v37, -v37, v39, v40
	v_div_fmas_f32 v37, v37, v50, v39
	v_div_fixup_f32 v7, v37, v7, 1.0
	v_mul_f32_e32 v25, v25, v7
	v_mul_f32_e32 v37, v41, v7
	v_mul_f32_e32 v39, v57, v7
	v_mul_f32_e32 v7, v73, v7
	v_add_u32_e32 v19, s30, v19
	v_add_u32_e32 v21, s30, v21
	v_add_u32_e32 v23, s30, v23
	v_add_u32_e32 v35, s30, v35
	v_or_b32_e32 v51, 17, v82
	s_waitcnt lgkmcnt(0)
	v_lshlrev_b32_e32 v2, 16, v2
	s_waitcnt lgkmcnt(0)
	v_lshlrev_b32_e32 v6, 16, v6
	s_waitcnt lgkmcnt(0)
	v_lshlrev_b32_e32 v24, 16, v24
	s_waitcnt lgkmcnt(0)
	v_lshlrev_b32_e32 v36, 16, v36
	v_mul_f32_e32 v2, v25, v2
	v_mul_f32_e32 v6, v37, v6
	v_mul_f32_e32 v24, v39, v24
	v_mul_f32_e32 v7, v7, v36
	v_bfe_u32 v25, v2, 16, 1
	v_bfe_u32 v36, v6, 16, 1
	v_bfe_u32 v37, v24, 16, 1
	v_bfe_u32 v39, v7, 16, 1
	v_add3_u32 v2, v2, v25, s61
	v_add3_u32 v6, v6, v36, s61
	v_add3_u32 v24, v24, v37, s61
	v_add3_u32 v7, v7, v39, s61
	global_store_short_d16_hi v[18:19], v2, off
	global_store_short_d16_hi v[20:21], v6, off
	global_store_short_d16_hi v[22:23], v24, off
	global_store_short_d16_hi v[34:35], v7, off
	ds_read_u16 v2, v206 offset:4096
	s_nop 0
	ds_read_u16 v40, v206 offset:4160
	ds_read_u16 v41, v206 offset:4224
	ds_read_u16 v50, v206 offset:4288
	ds_read_b128 v[18:21], v101 offset:192
	ds_read_b128 v[4:7], v101 offset:224
	v_mad_u64_u32 v[22:23], s[4:5], v51, s59, v[8:9]
	v_mad_u64_u32 v[24:25], s[4:5], v38, s62, v[10:11]
	s_waitcnt lgkmcnt(1)
	v_div_scale_f32 v52, s[4:5], v18, v18, 1.0
	v_rcp_f32_e32 v54, v52
	v_div_scale_f32 v53, vcc, 1.0, v18, 1.0
	v_add_u32_e32 v23, s2, v23
	v_fma_f32 v55, -v52, v54, 1.0
	v_fmac_f32_e32 v54, v55, v54
	v_mul_f32_e32 v55, v53, v54
	v_fma_f32 v56, -v52, v55, v53
	v_fmac_f32_e32 v55, v56, v54
	v_fma_f32 v52, -v52, v55, v53
	v_div_fmas_f32 v52, v52, v54, v55
	v_div_fixup_f32 v18, v52, v18, 1.0
	v_mul_f32_e32 v26, v26, v18
	v_mul_f32_e32 v42, v42, v18
	v_mul_f32_e32 v52, v58, v18
	v_mul_f32_e32 v18, v74, v18
	v_add_co_u32_e64 v22, s[4:5], s60, v22
	v_add_u32_e32 v25, s30, v25
	s_nop 0
	v_addc_co_u32_e64 v23, s[4:5], 0, v23, s[4:5]
	v_mad_u64_u32 v[34:35], s[4:5], v38, s62, v[14:15]
	v_mad_u64_u32 v[36:37], s[4:5], v38, s62, v[16:17]
	v_mad_u64_u32 v[38:39], s[4:5], v38, s62, v[12:13]
	v_add_u32_e32 v35, s30, v35
	v_add_u32_e32 v37, s30, v37
	v_add_u32_e32 v39, s30, v39
	s_waitcnt lgkmcnt(0)
; DI float bf2f(unsigned short u) { return __uint_as_float((unsigned)u << 16); }
; DI unsigned f2bf(float f) { unsigned u = __float_as_uint(f); return (u + 0x7fffu + ((u >> 16) & 1u)) >> 16; }
; DI int crow(int i, int hh) { return (i & 3) + 8 * (i >> 2) + 4 * hh; }
; DI void cross_unit(Ctx A_, LAS unsigned char* lds, int kvb, int hc, size_t row0, int nrows, int wave, int lane) {
;     ...
;     if (act) {
;         l += __shfl_xor(l, 32);
;         if (hh == 0) wsf[32 + r] = l;
;         float rl[16];
; #pragma unroll
;         for (int i = 0; i < 16; ++i) rl[i] = 1.0f / wsf[32 + crow(i, hh)];
; #pragma unroll
;         for (int nb = 0; nb < 4; ++nb)
; #pragma unroll
;             for (int i = 0; i < 16; ++i) {
;                 const int q = rg * 32 + crow(i, hh);
;                 if (q < nrows) { const size_t eo = (row0 + q) * PLD + hc * 256 + dvh * 128 + nb * 32 + r; Y_[(row0 + q) * YLD + C_YC + hc * 256 + dvh * 128 + nb * 32 + r] = (bf16)f2bf(o[nb][i] * rl[i] * bf2f(P[eo + C_ZC])); }
;             }
	v_lshlrev_b32_e32 v2, 16, v2
	s_waitcnt lgkmcnt(0)
	v_lshlrev_b32_e32 v40, 16, v40
	s_waitcnt lgkmcnt(0)
	v_lshlrev_b32_e32 v41, 16, v41
	s_waitcnt lgkmcnt(0)
	v_lshlrev_b32_e32 v50, 16, v50
	v_mul_f32_e32 v2, v26, v2
	v_mul_f32_e32 v26, v42, v40
	v_mul_f32_e32 v40, v52, v41
	v_mul_f32_e32 v18, v18, v50
	v_bfe_u32 v41, v2, 16, 1
	v_bfe_u32 v42, v26, 16, 1
	v_bfe_u32 v50, v40, 16, 1
	v_bfe_u32 v52, v18, 16, 1
	v_add3_u32 v2, v2, v41, s61
	v_add3_u32 v26, v26, v42, s61
	v_add3_u32 v40, v40, v50, s61
	v_add3_u32 v18, v18, v52, s61
	global_store_short_d16_hi v[24:25], v2, off
	global_store_short_d16_hi v[34:35], v26, off
	global_store_short_d16_hi v[36:37], v40, off
	global_store_short_d16_hi v[38:39], v18, off
	ds_read_u16 v2, v206 offset:4352
	s_nop 0
	ds_read_u16 v18, v206 offset:4416
	ds_read_u16 v26, v206 offset:4480
	ds_read_u16 v40, v206 offset:4544
	v_div_scale_f32 v42, s[4:5], v19, v19, 1.0
	v_rcp_f32_e32 v52, v42
	v_or_b32_e32 v41, 18, v82
	v_mad_u64_u32 v[22:23], s[4:5], v41, s59, v[8:9]
	v_mad_u64_u32 v[24:25], s[4:5], v51, s62, v[10:11]
	v_add_u32_e32 v23, s2, v23
	v_add_co_u32_e64 v22, s[4:5], s60, v22
	v_div_scale_f32 v50, vcc, 1.0, v19, 1.0
	s_nop 0
	v_addc_co_u32_e64 v23, s[4:5], 0, v23, s[4:5]
	v_mad_u64_u32 v[34:35], s[4:5], v51, s62, v[14:15]
	v_mad_u64_u32 v[36:37], s[4:5], v51, s62, v[16:17]
	v_mad_u64_u32 v[38:39], s[4:5], v51, s62, v[12:13]
	v_fma_f32 v51, -v42, v52, 1.0
	v_fmac_f32_e32 v52, v51, v52
	v_mul_f32_e32 v51, v50, v52
	v_fma_f32 v53, -v42, v51, v50
	v_fmac_f32_e32 v51, v53, v52
	v_fma_f32 v42, -v42, v51, v50
	v_div_fmas_f32 v42, v42, v52, v51
	v_div_fixup_f32 v19, v42, v19, 1.0
	v_mul_f32_e32 v27, v27, v19
	v_mul_f32_e32 v42, v43, v19
	v_mul_f32_e32 v43, v59, v19
	v_mul_f32_e32 v19, v75, v19
	v_add_u32_e32 v25, s30, v25
	v_add_u32_e32 v35, s30, v35
	v_add_u32_e32 v37, s30, v37
	v_add_u32_e32 v39, s30, v39
	s_waitcnt lgkmcnt(0)
	v_lshlrev_b32_e32 v2, 16, v2
	s_waitcnt lgkmcnt(0)
	v_lshlrev_b32_e32 v18, 16, v18
	s_waitcnt lgkmcnt(0)
	v_lshlrev_b32_e32 v26, 16, v26
	s_waitcnt lgkmcnt(0)
	v_lshlrev_b32_e32 v40, 16, v40
	v_mul_f32_e32 v2, v27, v2
	v_mul_f32_e32 v18, v42, v18
	v_mul_f32_e32 v26, v43, v26
	v_mul_f32_e32 v19, v19, v40
	v_bfe_u32 v27, v2, 16, 1
	v_bfe_u32 v40, v18, 16, 1
	v_bfe_u32 v42, v26, 16, 1
	v_bfe_u32 v43, v19, 16, 1
	v_add3_u32 v2, v2, v27, s61
	v_add3_u32 v18, v18, v40, s61
	v_add3_u32 v26, v26, v42, s61
	v_add3_u32 v19, v19, v43, s61
	global_store_short_d16_hi v[24:25], v2, off
	global_store_short_d16_hi v[34:35], v18, off
	global_store_short_d16_hi v[36:37], v26, off
	global_store_short_d16_hi v[38:39], v19, off
	ds_read_u16 v2, v206 offset:4608
	s_nop 0
	ds_read_u16 v36, v206 offset:4672
	ds_read_u16 v37, v206 offset:4736
	ds_read_u16 v38, v206 offset:4800
	v_div_scale_f32 v40, s[4:5], v20, v20, 1.0
	v_rcp_f32_e32 v43, v40
	v_or_b32_e32 v39, 19, v82
	v_mad_u64_u32 v[18:19], s[4:5], v39, s59, v[8:9]
	v_mad_u64_u32 v[22:23], s[4:5], v41, s62, v[10:11]
	v_add_u32_e32 v19, s2, v19
	v_add_co_u32_e64 v18, s[4:5], s60, v18
	v_div_scale_f32 v42, vcc, 1.0, v20, 1.0
	s_nop 0
	v_addc_co_u32_e64 v19, s[4:5], 0, v19, s[4:5]
	v_mad_u64_u32 v[24:25], s[4:5], v41, s62, v[14:15]
	v_mad_u64_u32 v[26:27], s[4:5], v41, s62, v[16:17]
	v_mad_u64_u32 v[34:35], s[4:5], v41, s62, v[12:13]
	v_fma_f32 v41, -v40, v43, 1.0
	v_fmac_f32_e32 v43, v41, v43
	v_mul_f32_e32 v41, v42, v43
	v_fma_f32 v50, -v40, v41, v42
	v_fmac_f32_e32 v41, v50, v43
	v_fma_f32 v40, -v40, v41, v42
	v_div_fmas_f32 v40, v40, v43, v41
	v_div_fixup_f32 v20, v40, v20, 1.0
	v_mul_f32_e32 v28, v28, v20
	v_mul_f32_e32 v40, v44, v20
	v_mul_f32_e32 v41, v60, v20
	v_mul_f32_e32 v20, v76, v20
	v_add_u32_e32 v23, s30, v23
	v_add_u32_e32 v25, s30, v25
	v_add_u32_e32 v27, s30, v27
	v_add_u32_e32 v35, s30, v35
	s_waitcnt lgkmcnt(0)
	v_lshlrev_b32_e32 v2, 16, v2
	s_waitcnt lgkmcnt(0)
	v_lshlrev_b32_e32 v36, 16, v36
	s_waitcnt lgkmcnt(0)
	v_lshlrev_b32_e32 v37, 16, v37
	s_waitcnt lgkmcnt(0)
	v_lshlrev_b32_e32 v38, 16, v38
	v_mul_f32_e32 v2, v28, v2
	v_mul_f32_e32 v28, v40, v36
	v_mul_f32_e32 v36, v41, v37
	v_mul_f32_e32 v20, v20, v38
	v_bfe_u32 v37, v2, 16, 1
	v_bfe_u32 v38, v28, 16, 1
	v_bfe_u32 v40, v36, 16, 1
	v_bfe_u32 v41, v20, 16, 1
	v_add3_u32 v2, v2, v37, s61
	v_add3_u32 v28, v28, v38, s61
	v_add3_u32 v36, v36, v40, s61
	v_add3_u32 v20, v20, v41, s61
	global_store_short_d16_hi v[22:23], v2, off
	global_store_short_d16_hi v[24:25], v28, off
	global_store_short_d16_hi v[26:27], v36, off
	global_store_short_d16_hi v[34:35], v20, off
	ds_read_u16 v2, v206 offset:4864
	s_nop 0
	ds_read_u16 v20, v206 offset:4928
	ds_read_u16 v28, v206 offset:4992
	ds_read_u16 v36, v206 offset:5056
	v_div_scale_f32 v38, s[4:5], v21, v21, 1.0
	v_rcp_f32_e32 v41, v38
	v_or_b32_e32 v37, 24, v82
	v_mad_u64_u32 v[18:19], s[4:5], v37, s59, v[8:9]
	v_mad_u64_u32 v[22:23], s[4:5], v39, s62, v[10:11]
	v_add_u32_e32 v19, s2, v19
	v_add_co_u32_e64 v18, s[4:5], s60, v18
	v_div_scale_f32 v40, vcc, 1.0, v21, 1.0
	s_nop 0
	v_addc_co_u32_e64 v19, s[4:5], 0, v19, s[4:5]
	v_mad_u64_u32 v[24:25], s[4:5], v39, s62, v[14:15]
	v_mad_u64_u32 v[26:27], s[4:5], v39, s62, v[16:17]
	v_mad_u64_u32 v[34:35], s[4:5], v39, s62, v[12:13]
	v_fma_f32 v39, -v38, v41, 1.0
	v_fmac_f32_e32 v41, v39, v41
	v_mul_f32_e32 v39, v40, v41
	v_fma_f32 v42, -v38, v39, v40
	v_fmac_f32_e32 v39, v42, v41
	v_fma_f32 v38, -v38, v39, v40
	v_div_fmas_f32 v38, v38, v41, v39
	v_div_fixup_f32 v21, v38, v21, 1.0
	v_mul_f32_e32 v29, v29, v21
	v_mul_f32_e32 v38, v45, v21
	v_mul_f32_e32 v39, v61, v21
	v_mul_f32_e32 v21, v77, v21
	v_add_u32_e32 v23, s30, v23
	v_add_u32_e32 v25, s30, v25
	v_add_u32_e32 v27, s30, v27
	v_add_u32_e32 v35, s30, v35
	s_waitcnt lgkmcnt(0)
; DI float bf2f(unsigned short u) { return __uint_as_float((unsigned)u << 16); }
; DI unsigned f2bf(float f) { unsigned u = __float_as_uint(f); return (u + 0x7fffu + ((u >> 16) & 1u)) >> 16; }
; DI int crow(int i, int hh) { return (i & 3) + 8 * (i >> 2) + 4 * hh; }
; DI void cross_unit(Ctx A_, LAS unsigned char* lds, int kvb, int hc, size_t row0, int nrows, int wave, int lane) {
;     ...
;     if (act) {
;         l += __shfl_xor(l, 32);
;         if (hh == 0) wsf[32 + r] = l;
;         float rl[16];
; #pragma unroll
;         for (int i = 0; i < 16; ++i) rl[i] = 1.0f / wsf[32 + crow(i, hh)];
; #pragma unroll
;         for (int nb = 0; nb < 4; ++nb)
; #pragma unroll
;             for (int i = 0; i < 16; ++i) {
;                 const int q = rg * 32 + crow(i, hh);
;                 if (q < nrows) { const size_t eo = (row0 + q) * PLD + hc * 256 + dvh * 128 + nb * 32 + r; Y_[(row0 + q) * YLD + C_YC + hc * 256 + dvh * 128 + nb * 32 + r] = (bf16)f2bf(o[nb][i] * rl[i] * bf2f(P[eo + C_ZC])); }
;             }
	v_lshlrev_b32_e32 v2, 16, v2
	s_waitcnt lgkmcnt(0)
	v_lshlrev_b32_e32 v20, 16, v20
	s_waitcnt lgkmcnt(0)
	v_lshlrev_b32_e32 v28, 16, v28
	s_waitcnt lgkmcnt(0)
	v_lshlrev_b32_e32 v36, 16, v36
	v_mul_f32_e32 v2, v29, v2
	v_mul_f32_e32 v20, v38, v20
	v_mul_f32_e32 v28, v39, v28
	v_mul_f32_e32 v21, v21, v36
	v_bfe_u32 v29, v2, 16, 1
	v_bfe_u32 v36, v20, 16, 1
	v_bfe_u32 v38, v28, 16, 1
	v_bfe_u32 v39, v21, 16, 1
	v_add3_u32 v2, v2, v29, s61
	v_add3_u32 v20, v20, v36, s61
	v_add3_u32 v28, v28, v38, s61
	v_add3_u32 v21, v21, v39, s61
	global_store_short_d16_hi v[22:23], v2, off
	global_store_short_d16_hi v[24:25], v20, off
	global_store_short_d16_hi v[26:27], v28, off
	global_store_short_d16_hi v[34:35], v21, off
	ds_read_u16 v2, v206 offset:6144
	s_nop 0
	ds_read_u16 v28, v206 offset:6208
	ds_read_u16 v29, v206 offset:6272
	ds_read_u16 v34, v206 offset:6336
	s_waitcnt lgkmcnt(0)
	v_div_scale_f32 v36, s[4:5], v4, v4, 1.0
	v_rcp_f32_e32 v39, v36
	v_or_b32_e32 v35, 25, v82
	v_mad_u64_u32 v[18:19], s[4:5], v35, s59, v[8:9]
	v_mad_u64_u32 v[20:21], s[4:5], v37, s62, v[10:11]
	v_add_u32_e32 v19, s2, v19
	v_add_co_u32_e64 v18, s[4:5], s60, v18
	v_div_scale_f32 v38, vcc, 1.0, v4, 1.0
	s_nop 0
	v_addc_co_u32_e64 v19, s[4:5], 0, v19, s[4:5]
	v_mad_u64_u32 v[22:23], s[4:5], v37, s62, v[14:15]
	v_mad_u64_u32 v[24:25], s[4:5], v37, s62, v[16:17]
	v_mad_u64_u32 v[26:27], s[4:5], v37, s62, v[12:13]
	v_fma_f32 v37, -v36, v39, 1.0
	v_fmac_f32_e32 v39, v37, v39
	v_mul_f32_e32 v37, v38, v39
	v_fma_f32 v40, -v36, v37, v38
	v_fmac_f32_e32 v37, v40, v39
	v_fma_f32 v36, -v36, v37, v38
	v_div_fmas_f32 v36, v36, v39, v37
	v_div_fixup_f32 v4, v36, v4, 1.0
	v_mul_f32_e32 v30, v30, v4
	v_mul_f32_e32 v36, v46, v4
	v_mul_f32_e32 v37, v62, v4
	v_mul_f32_e32 v4, v78, v4
	v_add_u32_e32 v21, s30, v21
	v_add_u32_e32 v23, s30, v23
	v_add_u32_e32 v25, s30, v25
	v_add_u32_e32 v27, s30, v27
	s_waitcnt lgkmcnt(0)
	v_lshlrev_b32_e32 v2, 16, v2
	s_waitcnt lgkmcnt(0)
	v_lshlrev_b32_e32 v28, 16, v28
	s_waitcnt lgkmcnt(0)
	v_lshlrev_b32_e32 v29, 16, v29
	s_waitcnt lgkmcnt(0)
	v_lshlrev_b32_e32 v34, 16, v34
	v_mul_f32_e32 v2, v30, v2
	v_mul_f32_e32 v28, v36, v28
	v_mul_f32_e32 v29, v37, v29
	v_mul_f32_e32 v4, v4, v34
	v_bfe_u32 v30, v2, 16, 1
	v_bfe_u32 v34, v28, 16, 1
	v_bfe_u32 v36, v29, 16, 1
	v_bfe_u32 v37, v4, 16, 1
	v_add3_u32 v2, v2, v30, s61
	v_add3_u32 v28, v28, v34, s61
	v_add3_u32 v29, v29, v36, s61
	v_add3_u32 v4, v4, v37, s61
	global_store_short_d16_hi v[20:21], v2, off
	global_store_short_d16_hi v[22:23], v28, off
	global_store_short_d16_hi v[24:25], v29, off
	global_store_short_d16_hi v[26:27], v4, off
	ds_read_u16 v2, v206 offset:6400
	s_nop 0
	ds_read_u16 v4, v206 offset:6464
	ds_read_u16 v28, v206 offset:6528
	ds_read_u16 v29, v206 offset:6592
	v_div_scale_f32 v34, s[4:5], v5, v5, 1.0
	v_rcp_f32_e32 v37, v34
	v_or_b32_e32 v30, 26, v82
	v_mad_u64_u32 v[18:19], s[4:5], v30, s59, v[8:9]
	v_mad_u64_u32 v[20:21], s[4:5], v35, s62, v[10:11]
	v_add_u32_e32 v19, s2, v19
	v_add_co_u32_e64 v18, s[4:5], s60, v18
	v_div_scale_f32 v36, vcc, 1.0, v5, 1.0
	s_nop 0
	v_addc_co_u32_e64 v19, s[4:5], 0, v19, s[4:5]
	v_mad_u64_u32 v[22:23], s[4:5], v35, s62, v[14:15]
	v_mad_u64_u32 v[24:25], s[4:5], v35, s62, v[16:17]
	v_mad_u64_u32 v[26:27], s[4:5], v35, s62, v[12:13]
	v_fma_f32 v35, -v34, v37, 1.0
	v_fmac_f32_e32 v37, v35, v37
	v_mul_f32_e32 v35, v36, v37
	v_fma_f32 v38, -v34, v35, v36
	v_fmac_f32_e32 v35, v38, v37
	v_fma_f32 v34, -v34, v35, v36
	v_div_fmas_f32 v34, v34, v37, v35
	v_div_fixup_f32 v5, v34, v5, 1.0
	v_mul_f32_e32 v31, v31, v5
	v_mul_f32_e32 v34, v47, v5
	v_mul_f32_e32 v35, v63, v5
	v_mul_f32_e32 v5, v79, v5
	v_add_u32_e32 v21, s30, v21
	v_add_u32_e32 v23, s30, v23
	v_add_u32_e32 v25, s30, v25
	v_add_u32_e32 v27, s30, v27
	s_waitcnt lgkmcnt(0)
	v_lshlrev_b32_e32 v2, 16, v2
	s_waitcnt lgkmcnt(0)
	v_lshlrev_b32_e32 v4, 16, v4
	s_waitcnt lgkmcnt(0)
	v_lshlrev_b32_e32 v28, 16, v28
	s_waitcnt lgkmcnt(0)
; DI float bf2f(unsigned short u) { return __uint_as_float((unsigned)u << 16); }
; DI unsigned f2bf(float f) { unsigned u = __float_as_uint(f); return (u + 0x7fffu + ((u >> 16) & 1u)) >> 16; }
; DI int crow(int i, int hh) { return (i & 3) + 8 * (i >> 2) + 4 * hh; }
; DI void cross_unit(Ctx A_, LAS unsigned char* lds, int kvb, int hc, size_t row0, int nrows, int wave, int lane) {
;     ...
; #pragma unroll
;         for (int nb = 0; nb < 4; ++nb)
; #pragma unroll
;             for (int i = 0; i < 16; ++i) {
;                 const int q = rg * 32 + crow(i, hh);
;                 if (q < nrows) { const size_t eo = (row0 + q) * PLD + hc * 256 + dvh * 128 + nb * 32 + r; Y_[(row0 + q) * YLD + C_YC + hc * 256 + dvh * 128 + nb * 32 + r] = (bf16)f2bf(o[nb][i] * rl[i] * bf2f(P[eo + C_ZC])); }
;             }
;     }
;     asm volatile("s_waitcnt vmcnt(0) lgkmcnt(0)" ::: "memory"); __builtin_amdgcn_s_barrier(); asm volatile("" ::: "memory");
	v_lshlrev_b32_e32 v29, 16, v29
	v_mul_f32_e32 v2, v31, v2
	v_mul_f32_e32 v4, v34, v4
	v_mul_f32_e32 v28, v35, v28
	v_mul_f32_e32 v5, v5, v29
	v_bfe_u32 v29, v2, 16, 1
	v_bfe_u32 v31, v4, 16, 1
	v_bfe_u32 v34, v28, 16, 1
	v_bfe_u32 v35, v5, 16, 1
	v_add3_u32 v2, v2, v29, s61
	v_add3_u32 v4, v4, v31, s61
	v_add3_u32 v28, v28, v34, s61
	v_add3_u32 v5, v5, v35, s61
	global_store_short_d16_hi v[20:21], v2, off
	global_store_short_d16_hi v[22:23], v4, off
	global_store_short_d16_hi v[24:25], v28, off
	global_store_short_d16_hi v[26:27], v5, off
	ds_read_u16 v2, v206 offset:6656
	s_nop 0
	ds_read_u16 v24, v206 offset:6720
	ds_read_u16 v25, v206 offset:6784
	ds_read_u16 v26, v206 offset:6848
	v_div_scale_f32 v28, s[4:5], v6, v6, 1.0
	v_rcp_f32_e32 v31, v28
	v_or_b32_e32 v27, 27, v82
	v_mad_u64_u32 v[4:5], s[4:5], v27, s59, v[8:9]
	v_mad_u64_u32 v[8:9], s[4:5], v30, s62, v[10:11]
	v_add_u32_e32 v5, s2, v5
	v_add_co_u32_e64 v4, s[4:5], s60, v4
	v_div_scale_f32 v29, vcc, 1.0, v6, 1.0
	s_nop 0
	v_addc_co_u32_e64 v5, s[4:5], 0, v5, s[4:5]
	v_mad_u64_u32 v[18:19], s[4:5], v30, s62, v[14:15]
	v_mad_u64_u32 v[20:21], s[4:5], v30, s62, v[16:17]
	v_mad_u64_u32 v[22:23], s[4:5], v30, s62, v[12:13]
	v_fma_f32 v30, -v28, v31, 1.0
	v_fmac_f32_e32 v31, v30, v31
	v_mul_f32_e32 v30, v29, v31
	v_fma_f32 v34, -v28, v30, v29
	v_fmac_f32_e32 v30, v34, v31
	v_fma_f32 v28, -v28, v30, v29
	v_div_fmas_f32 v28, v28, v31, v30
	v_div_fixup_f32 v6, v28, v6, 1.0
	v_mul_f32_e32 v28, v32, v6
	v_mul_f32_e32 v29, v48, v6
	v_mul_f32_e32 v30, v64, v6
	v_mul_f32_e32 v6, v80, v6
	v_add_u32_e32 v9, s30, v9
	v_add_u32_e32 v19, s30, v19
	v_add_u32_e32 v21, s30, v21
	v_add_u32_e32 v23, s30, v23
	v_mad_u64_u32 v[12:13], s[4:5], v27, s62, v[12:13]
	v_add_u32_e32 v13, s30, v13
	s_waitcnt lgkmcnt(0)
	v_lshlrev_b32_e32 v2, 16, v2
	s_waitcnt lgkmcnt(0)
	v_lshlrev_b32_e32 v24, 16, v24
	s_waitcnt lgkmcnt(0)
	v_lshlrev_b32_e32 v25, 16, v25
	s_waitcnt lgkmcnt(0)
	v_lshlrev_b32_e32 v26, 16, v26
	v_mul_f32_e32 v2, v28, v2
	v_mul_f32_e32 v24, v29, v24
	v_mul_f32_e32 v25, v30, v25
	v_mul_f32_e32 v6, v6, v26
	v_bfe_u32 v26, v2, 16, 1
	v_bfe_u32 v28, v24, 16, 1
	v_bfe_u32 v29, v25, 16, 1
	v_bfe_u32 v30, v6, 16, 1
	v_add3_u32 v2, v2, v26, s61
	v_add3_u32 v24, v24, v28, s61
	v_add3_u32 v25, v25, v29, s61
	v_add3_u32 v6, v6, v30, s61
	global_store_short_d16_hi v[8:9], v2, off
	global_store_short_d16_hi v[18:19], v24, off
	global_store_short_d16_hi v[20:21], v25, off
	global_store_short_d16_hi v[22:23], v6, off
	ds_read_u16 v2, v206 offset:6912
	s_nop 0
	ds_read_u16 v6, v206 offset:6976
	ds_read_u16 v18, v206 offset:7040
	ds_read_u16 v19, v206 offset:7104
	v_div_scale_f32 v20, s[4:5], v7, v7, 1.0
	v_rcp_f32_e32 v22, v20
	v_mad_u64_u32 v[8:9], s[4:5], v27, s62, v[14:15]
	v_div_scale_f32 v21, vcc, 1.0, v7, 1.0
	v_fma_f32 v14, -v20, v22, 1.0
	v_fmac_f32_e32 v22, v14, v22
	v_mul_f32_e32 v14, v21, v22
	v_fma_f32 v15, -v20, v14, v21
	v_fmac_f32_e32 v14, v15, v22
	v_fma_f32 v15, -v20, v14, v21
	v_div_fmas_f32 v14, v15, v22, v14
	v_div_fixup_f32 v7, v14, v7, 1.0
	v_mul_f32_e32 v14, v33, v7
	v_mad_u64_u32 v[4:5], s[4:5], v27, s62, v[10:11]
	v_mad_u64_u32 v[10:11], s[4:5], v27, s62, v[16:17]
	v_mul_f32_e32 v15, v49, v7
	v_mul_f32_e32 v16, v65, v7
	v_mul_f32_e32 v7, v81, v7
	v_add_u32_e32 v5, s30, v5
	v_add_u32_e32 v9, s30, v9
	v_add_u32_e32 v11, s30, v11
	s_waitcnt lgkmcnt(0)
	v_lshlrev_b32_e32 v2, 16, v2
	s_waitcnt lgkmcnt(0)
	v_lshlrev_b32_e32 v6, 16, v6
	s_waitcnt lgkmcnt(0)
	v_lshlrev_b32_e32 v17, 16, v18
	s_waitcnt lgkmcnt(0)
	v_lshlrev_b32_e32 v18, 16, v19
	v_mul_f32_e32 v2, v14, v2
	v_mul_f32_e32 v6, v15, v6
	v_mul_f32_e32 v14, v16, v17
	v_mul_f32_e32 v7, v7, v18
	v_bfe_u32 v15, v2, 16, 1
	v_bfe_u32 v16, v6, 16, 1
	v_bfe_u32 v17, v14, 16, 1
	v_bfe_u32 v18, v7, 16, 1
	v_add3_u32 v2, v2, v15, s61
	v_add3_u32 v6, v6, v16, s61
	v_add3_u32 v14, v14, v17, s61
	v_add3_u32 v7, v7, v18, s61
	global_store_short_d16_hi v[4:5], v2, off
	global_store_short_d16_hi v[8:9], v6, off
	global_store_short_d16_hi v[10:11], v14, off
	global_store_short_d16_hi v[12:13], v7, off
	s_waitcnt vmcnt(0) lgkmcnt(0)
	s_barrier

; DI float bf2f(unsigned short u) { return __uint_as_float((unsigned)u << 16); }
; DI unsigned f2bf(float f) { unsigned u = __float_as_uint(f); return (u + 0x7fffu + ((u >> 16) & 1u)) >> 16; }
; DI void cross_unit(Ctx A_, LAS unsigned char* lds, int kvb, int hc, size_t row0, int nrows, int wave, int lane) {
;     ...
;         asm volatile("s_waitcnt vmcnt(0) lgkmcnt(0)" ::: "memory"); __builtin_amdgcn_s_barrier(); asm volatile("" ::: "memory");
;         if (t + 1 < 8) load_tile(lds + ((t + 1) & 1) * BUF, Kg, Vg, (t + 1) * 32, wave, lane);
;     ...
;                 if (q < nrows) { const size_t eo = (row0 + q) * PLD + hc * 256 + dvh * 128 + nb * 32 + r; Y_[(row0 + q) * YLD + C_YC + hc * 256 + dvh * 128 + nb * 32 + r] = (bf16)f2bf(o[nb][i] * rl[i] * bf2f(P[eo + C_ZC])); }
.LctC_s:
	v_readfirstlane_b32 s34, v0
	s_lshr_b32 s34, s34, 6
	s_and_b32 s63, s34, 3
	s_lshl_b32 s63, s63, 5
	s_add_i32 s98, s98, s63
	s_lshr_b32 s63, s34, 2
	s_lshl_b32 s63, s63, 8
	s_lshl_b32 s100, s100, 9
	s_add_i32 s100, s100, s63
	s_add_i32 s100, s100, 0x5000
	s_mul_hi_u32 s99, s98, 0x5800
	s_mul_i32 s98, s98, 0x5800
	v_readlane_b32 s63, v255, 9
	v_readlane_b32 s101, v255, 10
	v_and_b32_e32 v206, 63, v0
	v_lshrrev_b32_e32 v207, 4, v206
	s_add_u32 s98, s98, s63
	s_addc_u32 s99, s99, s101
	s_add_u32 s98, s98, s100
	s_addc_u32 s99, s99, 0
	v_mul_u32_u24_e32 v207, 0x5800, v207
	v_and_b32_e32 v206, 15, v206
	v_lshl_or_b32 v206, v206, 4, v207
	s_lshl_b32 s34, s34, 13
	s_add_i32 s34, s34, 0x10000
	s_mov_b32 s101, m0
	s_mov_b32 m0, s34
	s_nop 0
	global_load_lds_dwordx4 v206, s[98:99]
	s_add_u32 s98, s98, 0x16000
	s_addc_u32 s99, s99, 0
	s_add_i32 s34, s34, 0x400
	s_mov_b32 m0, s34
	s_nop 0
	global_load_lds_dwordx4 v206, s[98:99]
	s_add_u32 s98, s98, 0x16000
	s_addc_u32 s99, s99, 0
	s_add_i32 s34, s34, 0x400
	s_mov_b32 m0, s34
	s_nop 0
	global_load_lds_dwordx4 v206, s[98:99]
	s_add_u32 s98, s98, 0x16000
	s_addc_u32 s99, s99, 0
	s_add_i32 s34, s34, 0x400
	s_mov_b32 m0, s34
	s_nop 0
	global_load_lds_dwordx4 v206, s[98:99]
	s_add_u32 s98, s98, 0x16000
	s_addc_u32 s99, s99, 0
	s_add_i32 s34, s34, 0x400
	s_mov_b32 m0, s34
	s_nop 0
	global_load_lds_dwordx4 v206, s[98:99]
	s_add_u32 s98, s98, 0x16000
	s_addc_u32 s99, s99, 0
	s_add_i32 s34, s34, 0x400
	s_mov_b32 m0, s34
	s_nop 0
	global_load_lds_dwordx4 v206, s[98:99]
	s_add_u32 s98, s98, 0x16000
	s_addc_u32 s99, s99, 0
	s_add_i32 s34, s34, 0x400
	s_mov_b32 m0, s34
	s_nop 0
	global_load_lds_dwordx4 v206, s[98:99]
	s_add_u32 s98, s98, 0x16000
	s_addc_u32 s99, s99, 0
	s_add_i32 s34, s34, 0x400
	s_mov_b32 m0, s34
	s_nop 0
	global_load_lds_dwordx4 v206, s[98:99]
	s_mov_b32 m0, s101
